# phase F filler (next layer's S5 table build on workgroups 64..255): the 8-step inner loop's 21 later loads hoisted beside the first group into fresh registers with counted waits; the filler no longer
# speedup vs baseline: 1.0170x; 1.0058x over previous
; __device__ __forceinline__ void s5_tables(KArgs& a, int l, int blk0, int nblk) {
;     ...
;     for (size_t e = gt; e < (size_t)32 * 2 * 32 * 16 * 4; e += gn) {
;         const int mq = (int)(e & 3), n = (int)((e >> 2) & 15), d = (int)((e >> 6) & 31), dir = (int)((e >> 11) & 1), gI = (int)(e >> 12);
;         const int dg = dir * 32 + gI; f32x4 acc = {0.f, 0.f, 0.f, 0.f};
; #pragma unroll 8
;         for (int p = 0; p < 64; ++p) {
;             const f32x2 ap = AP[((size_t)dg * 64 + p) * 33 + d];
;             const f32x4 b01 = *(const f32x4*)(BB + ((size_t)dg * 64 + p) * 16 + 4 * mq), b23 = *(const f32x4*)(BB + ((size_t)dg * 64 + p) * 16 + 4 * mq + 2);
;             const float cr = cre[((size_t)dg * 16 + n) * 64 + p], ci = cim[((size_t)dg * 16 + n) * 64 + p];
;             const float wr_ = cr * ap.x - ci * ap.y, wi_ = cr * ap.y + ci * ap.x;
;             acc[0] += wr_ * b01[0] - wi_ * b01[1]; acc[1] += wr_ * b01[2] - wi_ * b01[3];
;             acc[2] += wr_ * b23[0] - wi_ * b23[1]; acc[3] += wr_ * b23[2] - wi_ * b23[3];
;         }
;         *(f32x4*)(KT + ((((size_t)gI * 2 + dir) * 32 + d) * 16 + n) * 16 + 4 * mq) = acc;
.LBB0_900:
	v_lshl_add_u64 v[10:11], v[32:33], 0, s[58:59]
	v_lshl_add_u64 v[18:19], v[34:35], 0, s[58:59]
	global_load_dwordx2 v[52:53], v[38:39], off offset:-1056
	global_load_dwordx4 v[44:47], v[36:37], off offset:-496
	global_load_dwordx4 v[48:51], v[36:37], off offset:-512
	global_load_dwordx4 v[6:9], v[10:11], off offset:16
	global_load_dwordx4 v[14:17], v[10:11], off
	s_nop 0
	global_load_dwordx4 v[10:13], v[18:19], off offset:16
	s_nop 0
	global_load_dwordx4 v[18:21], v[18:19], off
	s_add_u32 s58, s58, 32
	s_addc_u32 s59, s59, 0
	s_cmpk_eq_i32 s58, 0x100
	global_load_dwordx2 v[60:61], v[38:39], off offset:-792
	global_load_dwordx4 v[62:65], v[36:37], off offset:-368
	global_load_dwordx4 v[66:69], v[36:37], off offset:-384
	global_load_dwordx2 v[70:71], v[38:39], off offset:-528
	global_load_dwordx4 v[72:75], v[36:37], off offset:-240
	global_load_dwordx4 v[76:79], v[36:37], off offset:-256
	global_load_dwordx2 v[80:81], v[38:39], off offset:-264
	global_load_dwordx4 v[82:85], v[36:37], off offset:-112
	global_load_dwordx4 v[86:89], v[36:37], off offset:-128
	global_load_dwordx2 v[90:91], v[38:39], off
	global_load_dwordx4 v[92:95], v[36:37], off offset:16
	global_load_dwordx4 v[96:99], v[36:37], off
	global_load_dwordx2 v[100:101], v[38:39], off offset:264
	global_load_dwordx4 v[102:105], v[36:37], off offset:144
	global_load_dwordx4 v[106:109], v[36:37], off offset:128
	global_load_dwordx2 v[110:111], v[38:39], off offset:528
	global_load_dwordx4 v[112:115], v[36:37], off offset:272
	global_load_dwordx4 v[116:119], v[36:37], off offset:256
	global_load_dwordx2 v[120:121], v[38:39], off offset:792
	global_load_dwordx4 v[122:125], v[36:37], off offset:400
	global_load_dwordx4 v[126:129], v[36:37], off offset:384
	s_waitcnt vmcnt(21)
	v_mov_b32_e32 v59, v50
	v_mov_b32_e32 v50, v49
	v_pk_mul_f32 v[54:55], v[52:53], v[18:19] op_sel:[1, 0] op_sel_hi:[0, 0]
	v_pk_fma_f32 v[56:57], v[52:53], v[14:15], v[54:55] op_sel_hi:[1, 0, 1] neg_lo:[0, 0, 1] neg_hi:[0, 0, 1]
	v_pk_fma_f32 v[52:53], v[52:53], v[14:15], v[54:55] op_sel_hi:[1, 0, 1]
	v_mov_b32_e32 v54, v56
	v_mov_b32_e32 v55, v53
	v_pk_mul_f32 v[46:47], v[46:47], v[54:55]
	v_mov_b32_e32 v58, v48
	v_pk_mul_f32 v[48:49], v[50:51], v[52:53] op_sel:[0, 1]
	v_mul_f32_e32 v44, v44, v56
	v_mul_f32_e32 v50, v45, v53
	v_mov_b32_e32 v45, v46
	v_mov_b32_e32 v51, v47
	v_pk_fma_f32 v[46:47], v[58:59], v[56:57], v[48:49] op_sel_hi:[1, 0, 1] neg_lo:[0, 0, 1] neg_hi:[0, 0, 1]
	v_pk_add_f32 v[44:45], v[44:45], v[50:51] neg_lo:[0, 1] neg_hi:[0, 1]
	v_pk_add_f32 v[50:51], v[2:3], v[46:47]
	v_pk_add_f32 v[48:49], v[4:5], v[44:45]
	v_mov_b32_e32 v0, v17
	s_waitcnt vmcnt(20)
	v_pk_mul_f32 v[18:19], v[60:61], v[18:19] op_sel:[1, 1] op_sel_hi:[0, 1]
	v_pk_fma_f32 v[54:55], v[60:61], v[14:15], v[18:19] op_sel:[0, 1, 0] neg_lo:[0, 0, 1] neg_hi:[0, 0, 1]
	v_pk_fma_f32 v[14:15], v[60:61], v[14:15], v[18:19] op_sel:[0, 1, 0]
	v_mov_b32_e32 v18, v54
	v_mov_b32_e32 v19, v15
	s_waitcnt vmcnt(18)
	v_mov_b32_e32 v53, v68
	v_mov_b32_e32 v46, v67
	v_pk_mul_f32 v[4:5], v[64:65], v[18:19]
	v_mov_b32_e32 v52, v66
	v_mov_b32_e32 v47, v69
	v_pk_mul_f32 v[44:45], v[46:47], v[14:15] op_sel:[0, 1]
	v_mul_f32_e32 v2, v62, v54
	v_mul_f32_e32 v14, v63, v15
	v_mov_b32_e32 v3, v4
	v_mov_b32_e32 v15, v5
	v_pk_fma_f32 v[4:5], v[52:53], v[54:55], v[44:45] op_sel_hi:[1, 0, 1] neg_lo:[0, 0, 1] neg_hi:[0, 0, 1]
	v_pk_add_f32 v[2:3], v[2:3], v[14:15] neg_lo:[0, 1] neg_hi:[0, 1]
	v_pk_add_f32 v[18:19], v[50:51], v[4:5]
	v_pk_add_f32 v[14:15], v[48:49], v[2:3]
	s_waitcnt vmcnt(17)
	v_pk_mul_f32 v[50:51], v[70:71], v[20:21] op_sel:[1, 0] op_sel_hi:[0, 0]
	v_pk_fma_f32 v[52:53], v[70:71], v[16:17], v[50:51] op_sel_hi:[1, 0, 1] neg_lo:[0, 0, 1] neg_hi:[0, 0, 1]
	v_pk_fma_f32 v[48:49], v[70:71], v[16:17], v[50:51] op_sel_hi:[1, 0, 1]
	v_mov_b32_e32 v50, v52
	v_mov_b32_e32 v51, v49
	s_waitcnt vmcnt(15)
	v_mov_b32_e32 v55, v78
	v_mov_b32_e32 v46, v77
	v_pk_mul_f32 v[4:5], v[74:75], v[50:51]
	v_mov_b32_e32 v54, v76
	v_mov_b32_e32 v47, v79
	v_pk_mul_f32 v[44:45], v[46:47], v[48:49] op_sel:[0, 1]
	v_mul_f32_e32 v2, v72, v52
	v_mul_f32_e32 v46, v73, v49
	v_mov_b32_e32 v3, v4
	v_mov_b32_e32 v47, v5
	v_pk_fma_f32 v[4:5], v[54:55], v[52:53], v[44:45] op_sel_hi:[1, 0, 1] neg_lo:[0, 0, 1] neg_hi:[0, 0, 1]
	v_pk_add_f32 v[2:3], v[2:3], v[46:47] neg_lo:[0, 1] neg_hi:[0, 1]
	v_pk_add_f32 v[18:19], v[18:19], v[4:5]
	v_pk_add_f32 v[14:15], v[14:15], v[2:3]
	v_mov_b32_e32 v16, v21
	s_waitcnt vmcnt(14)
	v_pk_mul_f32 v[16:17], v[80:81], v[16:17] op_sel:[1, 0] op_sel_hi:[0, 0]
	v_pk_fma_f32 v[20:21], v[80:81], v[0:1], v[16:17] op_sel_hi:[1, 0, 1] neg_lo:[0, 0, 1] neg_hi:[0, 0, 1]
	v_pk_fma_f32 v[16:17], v[80:81], v[0:1], v[16:17] op_sel_hi:[1, 0, 1]
	v_mov_b32_e32 v48, v20
	v_mov_b32_e32 v49, v17
	s_waitcnt vmcnt(12)
; __device__ __forceinline__ void s5_tables(KArgs& a, int l, int blk0, int nblk) {
;     ...
; #pragma unroll 8
;         for (int p = 0; p < 64; ++p) {
;             const f32x2 ap = AP[((size_t)dg * 64 + p) * 33 + d];
;             const f32x4 b01 = *(const f32x4*)(BB + ((size_t)dg * 64 + p) * 16 + 4 * mq), b23 = *(const f32x4*)(BB + ((size_t)dg * 64 + p) * 16 + 4 * mq + 2);
;             const float cr = cre[((size_t)dg * 16 + n) * 64 + p], ci = cim[((size_t)dg * 16 + n) * 64 + p];
;             const float wr_ = cr * ap.x - ci * ap.y, wi_ = cr * ap.y + ci * ap.x;
;             acc[0] += wr_ * b01[0] - wi_ * b01[1]; acc[1] += wr_ * b01[2] - wi_ * b01[3];
;             acc[2] += wr_ * b23[0] - wi_ * b23[1]; acc[3] += wr_ * b23[2] - wi_ * b23[3];
;         }
;         *(f32x4*)(KT + ((((size_t)gI * 2 + dir) * 32 + d) * 16 + n) * 16 + 4 * mq) = acc;
	v_mov_b32_e32 v51, v88
	v_mov_b32_e32 v46, v87
	v_pk_mul_f32 v[4:5], v[84:85], v[48:49]
	v_mov_b32_e32 v50, v86
	v_mov_b32_e32 v47, v89
	v_pk_mul_f32 v[44:45], v[46:47], v[16:17] op_sel:[0, 1]
	v_mul_f32_e32 v2, v82, v20
	v_mul_f32_e32 v16, v83, v17
	v_mov_b32_e32 v3, v4
	v_mov_b32_e32 v17, v5
	v_pk_fma_f32 v[4:5], v[50:51], v[20:21], v[44:45] op_sel_hi:[1, 0, 1] neg_lo:[0, 0, 1] neg_hi:[0, 0, 1]
	v_pk_add_f32 v[2:3], v[2:3], v[16:17] neg_lo:[0, 1] neg_hi:[0, 1]
	v_pk_add_f32 v[18:19], v[18:19], v[4:5]
	v_pk_add_f32 v[20:21], v[14:15], v[2:3]
	v_mov_b32_e32 v0, v9
	s_waitcnt vmcnt(11)
	v_pk_mul_f32 v[46:47], v[90:91], v[10:11] op_sel:[1, 0] op_sel_hi:[0, 0]
	v_pk_fma_f32 v[48:49], v[90:91], v[6:7], v[46:47] op_sel_hi:[1, 0, 1] neg_lo:[0, 0, 1] neg_hi:[0, 0, 1]
	v_pk_fma_f32 v[44:45], v[90:91], v[6:7], v[46:47] op_sel_hi:[1, 0, 1]
	v_mov_b32_e32 v46, v48
	v_mov_b32_e32 v47, v45
	s_waitcnt vmcnt(9)
	v_mov_b32_e32 v51, v98
	v_mov_b32_e32 v16, v97
	v_pk_mul_f32 v[4:5], v[94:95], v[46:47]
	v_mov_b32_e32 v50, v96
	v_mov_b32_e32 v17, v99
	v_pk_mul_f32 v[14:15], v[16:17], v[44:45] op_sel:[0, 1]
	v_mul_f32_e32 v2, v92, v48
	v_mul_f32_e32 v16, v93, v45
	v_mov_b32_e32 v3, v4
	v_mov_b32_e32 v17, v5
	v_pk_fma_f32 v[4:5], v[50:51], v[48:49], v[14:15] op_sel_hi:[1, 0, 1] neg_lo:[0, 0, 1] neg_hi:[0, 0, 1]
	v_pk_add_f32 v[2:3], v[2:3], v[16:17] neg_lo:[0, 1] neg_hi:[0, 1]
	v_pk_add_f32 v[18:19], v[18:19], v[4:5]
	v_pk_add_f32 v[20:21], v[20:21], v[2:3]
	s_waitcnt vmcnt(8)
	v_pk_mul_f32 v[10:11], v[100:101], v[10:11] op_sel:[1, 1] op_sel_hi:[0, 1]
	v_pk_fma_f32 v[46:47], v[100:101], v[6:7], v[10:11] op_sel:[0, 1, 0] neg_lo:[0, 0, 1] neg_hi:[0, 0, 1]
	v_pk_fma_f32 v[6:7], v[100:101], v[6:7], v[10:11] op_sel:[0, 1, 0]
	v_mov_b32_e32 v10, v46
	v_mov_b32_e32 v11, v7
	s_waitcnt vmcnt(6)
	v_mov_b32_e32 v45, v108
	v_mov_b32_e32 v16, v107
	v_pk_mul_f32 v[4:5], v[104:105], v[10:11]
	v_mov_b32_e32 v44, v106
	v_mov_b32_e32 v17, v109
	v_pk_mul_f32 v[14:15], v[16:17], v[6:7] op_sel:[0, 1]
	v_mul_f32_e32 v2, v102, v46
	v_mul_f32_e32 v6, v103, v7
	v_mov_b32_e32 v3, v4
	v_mov_b32_e32 v7, v5
	v_pk_fma_f32 v[4:5], v[44:45], v[46:47], v[14:15] op_sel_hi:[1, 0, 1] neg_lo:[0, 0, 1] neg_hi:[0, 0, 1]
	v_pk_add_f32 v[2:3], v[2:3], v[6:7] neg_lo:[0, 1] neg_hi:[0, 1]
	v_pk_add_f32 v[10:11], v[18:19], v[4:5]
	v_pk_add_f32 v[6:7], v[20:21], v[2:3]
	s_waitcnt vmcnt(5)
	v_pk_mul_f32 v[20:21], v[110:111], v[12:13] op_sel:[1, 0] op_sel_hi:[0, 0]
	v_pk_fma_f32 v[44:45], v[110:111], v[8:9], v[20:21] op_sel_hi:[1, 0, 1] neg_lo:[0, 0, 1] neg_hi:[0, 0, 1]
	v_pk_fma_f32 v[18:19], v[110:111], v[8:9], v[20:21] op_sel_hi:[1, 0, 1]
	v_mov_b32_e32 v20, v44
	v_mov_b32_e32 v21, v19
	s_waitcnt vmcnt(3)
	v_mov_b32_e32 v47, v118
	v_mov_b32_e32 v16, v117
	v_pk_mul_f32 v[4:5], v[114:115], v[20:21]
	v_mov_b32_e32 v46, v116
	v_mov_b32_e32 v17, v119
	v_pk_mul_f32 v[14:15], v[16:17], v[18:19] op_sel:[0, 1]
	v_mul_f32_e32 v2, v112, v44
	v_mul_f32_e32 v16, v113, v19
	v_mov_b32_e32 v3, v4
	v_mov_b32_e32 v17, v5
	v_pk_fma_f32 v[4:5], v[46:47], v[44:45], v[14:15] op_sel_hi:[1, 0, 1] neg_lo:[0, 0, 1] neg_hi:[0, 0, 1]
	v_pk_add_f32 v[2:3], v[2:3], v[16:17] neg_lo:[0, 1] neg_hi:[0, 1]
	v_pk_add_f32 v[10:11], v[10:11], v[4:5]
	v_pk_add_f32 v[6:7], v[6:7], v[2:3]
	v_mov_b32_e32 v8, v13
	v_lshl_add_u64 v[36:37], v[36:37], 0, s[10:11]
	v_lshl_add_u64 v[38:39], v[38:39], 0, s[12:13]
	s_waitcnt vmcnt(2)
	v_pk_mul_f32 v[8:9], v[120:121], v[8:9] op_sel:[1, 0] op_sel_hi:[0, 0]
	v_pk_fma_f32 v[12:13], v[120:121], v[0:1], v[8:9] op_sel_hi:[1, 0, 1] neg_lo:[0, 0, 1] neg_hi:[0, 0, 1]
	v_pk_fma_f32 v[8:9], v[120:121], v[0:1], v[8:9] op_sel_hi:[1, 0, 1]
	v_mov_b32_e32 v18, v12
	v_mov_b32_e32 v19, v9
	s_waitcnt vmcnt(0)
	v_mov_b32_e32 v21, v128
	v_mov_b32_e32 v16, v127
	v_pk_mul_f32 v[4:5], v[124:125], v[18:19]
	v_mov_b32_e32 v20, v126
	v_mov_b32_e32 v17, v129
	v_pk_mul_f32 v[14:15], v[16:17], v[8:9] op_sel:[0, 1]
	v_mul_f32_e32 v2, v122, v12
	v_mul_f32_e32 v8, v123, v9
	v_mov_b32_e32 v3, v4
	v_mov_b32_e32 v9, v5
	v_pk_fma_f32 v[12:13], v[20:21], v[12:13], v[14:15] op_sel_hi:[1, 0, 1] neg_lo:[0, 0, 1] neg_hi:[0, 0, 1]
	v_pk_add_f32 v[2:3], v[2:3], v[8:9] neg_lo:[0, 1] neg_hi:[0, 1]
	s_nop 0
	v_pk_add_f32 v[4:5], v[6:7], v[2:3]
	v_pk_add_f32 v[2:3], v[10:11], v[12:13]
	s_cbranch_scc0 .LBB0_900
	v_lshrrev_b64 v[6:7], 6, v[30:31]
	v_and_b32_e32 v8, 31, v41
	v_and_b32_e32 v6, 0xffffffc0, v6
	v_and_b32_e32 v7, 0x3fffff, v7
	v_or3_b32 v6, v6, v29, v8
	v_and_b32_e32 v0, 15, v42
	v_lshlrev_b64 v[6:7], 10, v[6:7]
	v_lshl_add_u64 v[6:7], s[40:41], 0, v[6:7]
	v_lshlrev_b32_e32 v0, 6, v0
	v_lshl_add_u64 v[6:7], v[6:7], 0, v[0:1]
	v_mov_b32_e32 v29, v1
	v_lshl_add_u64 v[6:7], v[6:7], 0, v[28:29]
	global_store_dwordx4 v[6:7], v[2:5], off
	v_add_u32_e32 v40, 24, v40
	s_nop 0
	v_lshl_add_u64 v[2:3], v[30:31], 0, s[0:1]
	s_mov_b64 s[0:1], 0x7fff
	v_cmp_lt_u64_e32 vcc, s[0:1], v[30:31]
	s_or_b64 s[48:49], vcc, s[48:49]
	v_mov_b64_e32 v[30:31], v[2:3]
	s_andn2_b64 exec, exec, s[48:49]
	s_cbranch_execnz .LBB0_899
